# v47: XCD-local barriers at the out-proj->up and down->gate boundaries when the virtual-id bijection holds (no L2 write-back, no chip-wide stage; L1 acquire kept) (v45 + local barriers)
# speedup vs baseline: 1.0060x; 1.0038x over previous
.LBB0_172:
	s_or_b64 exec, exec, s[0:1]
	s_and_b32 s40, s46, 7
	s_barrier
	s_mov_b64 s[38:39], exec
	v_readlane_b32 s0, v252, 2
	v_readlane_b32 s1, v252, 3
	s_and_b64 s[0:1], s[38:39], s[0:1]
	s_mov_b64 exec, s[0:1]
	s_cbranch_execz .LBB0_174
	v_mov_b32_e32 v0, 0xa0000
	global_load_dword v2, v0, s[10:11] offset:1024 sc1
	global_load_dword v3, v0, s[10:11] offset:1280 sc1
	global_load_dword v4, v0, s[10:11] offset:1536 sc1
	global_load_dword v5, v0, s[10:11] offset:1792 sc1
	global_load_dword v6, v0, s[10:11] offset:2048 sc1
	global_load_dword v7, v0, s[10:11] offset:2304 sc1
	global_load_dword v8, v0, s[10:11] offset:2560 sc1
	global_load_dword v9, v0, s[10:11] offset:2816 sc1
	global_load_dword v11, v0, s[10:11] offset:3072 sc1
	global_load_dword v12, v0, s[10:11] offset:3328 sc1
	global_load_dword v13, v0, s[10:11] offset:3584 sc1
	s_nop 0
	global_load_dword v0, v0, s[10:11] offset:3840 sc1
	v_mov_b32_e32 v14, 0xa1000
	global_load_dword v15, v14, s[10:11] sc1
	global_load_dword v16, v14, s[10:11] offset:256 sc1
	global_load_dword v17, v14, s[10:11] offset:512 sc1
	s_nop 0
	global_load_dword v14, v14, s[10:11] offset:768 sc1
	s_cmp_eq_u32 s40, 0
	s_cselect_b64 s[42:43], -1, 0
	s_lshr_b32 s16, s46, 3
	v_add_u32_e32 v1, s33, v1
	v_mov_b32_e32 v18, s2
	s_add_i32 s41, 0, 0x261e0
	s_waitcnt vmcnt(15)
	v_cmp_eq_u32_e32 vcc, s16, v2
	s_waitcnt vmcnt(14)
	v_cmp_eq_u32_e64 s[0:1], s16, v3
	s_and_b64 s[42:43], s[42:43], vcc
	s_waitcnt vmcnt(13)
	v_cmp_eq_u32_e64 s[4:5], s16, v4
	s_and_b64 s[0:1], s[42:43], s[0:1]
	s_waitcnt vmcnt(12)
	v_cmp_eq_u32_e64 s[6:7], s16, v5
	s_and_b64 s[0:1], s[0:1], s[4:5]
	s_waitcnt vmcnt(11)
	v_cmp_eq_u32_e64 s[36:37], s16, v6
	s_and_b64 s[0:1], s[0:1], s[6:7]
	s_waitcnt vmcnt(10)
	v_cmp_eq_u32_e64 s[12:13], s16, v7
	s_and_b64 s[0:1], s[0:1], s[36:37]
	s_waitcnt vmcnt(9)
	v_cmp_eq_u32_e64 s[14:15], s16, v8
	s_and_b64 s[0:1], s[0:1], s[12:13]
	s_waitcnt vmcnt(8)
	v_cmp_eq_u32_e64 s[16:17], s16, v9
	s_and_b64 s[0:1], s[0:1], s[14:15]
	s_waitcnt vmcnt(7)
	v_cmp_eq_u32_e64 s[18:19], 0, v11
	s_and_b64 s[0:1], s[0:1], s[16:17]
	s_waitcnt vmcnt(6)
	v_cmp_eq_u32_e64 s[20:21], 0, v12
	s_and_b64 s[0:1], s[0:1], s[18:19]
	s_waitcnt vmcnt(5)
	v_cmp_eq_u32_e64 s[22:23], 0, v13
	s_and_b64 s[0:1], s[0:1], s[20:21]
	s_waitcnt vmcnt(4)
	v_cmp_eq_u32_e64 s[24:25], 0, v0
	s_and_b64 s[0:1], s[0:1], s[22:23]
	s_waitcnt vmcnt(3)
	v_cmp_eq_u32_e64 s[26:27], 0, v15
	s_and_b64 s[0:1], s[0:1], s[24:25]
	s_waitcnt vmcnt(2)
	v_cmp_eq_u32_e64 s[28:29], 0, v16
	s_and_b64 s[0:1], s[0:1], s[26:27]
	s_waitcnt vmcnt(1)
	v_cmp_eq_u32_e64 s[30:31], 0, v17
	s_and_b64 s[0:1], s[0:1], s[28:29]
	s_waitcnt vmcnt(0)
	v_cmp_eq_u32_e64 s[34:35], 0, v14
	s_and_b64 s[0:1], s[0:1], s[30:31]
	s_and_b64 vcc, s[0:1], s[34:35]
	v_writelane_b32 v255, vcc_lo, 40
	v_cndmask_b32_e32 v0, v18, v1, vcc
	v_mov_b32_e32 v1, s41
	ds_write_b32 v1, v0

.LBB0_683:
	s_andn2_saveexec_b64 s[4:5], s[4:5]
	s_cbranch_execz .LBB0_703
	s_mov_b64 s[4:5], exec
	v_readlane_b32 s99, v255, 40
	s_bitcmp1_b32 s99, 0
	s_cbranch_scc1 .Lxl_5
	buffer_wbl2 sc1
	s_waitcnt lgkmcnt(0)
	s_waitcnt vmcnt(0)
	v_mbcnt_lo_u32_b32 v1, s4, 0
	v_mbcnt_hi_u32_b32 v1, s5, v1
	v_cmp_eq_u32_e32 vcc, 0, v1
	s_and_saveexec_b64 s[6:7], vcc
	s_cbranch_execz .LBB0_686
	s_bcnt1_i32_b64 s4, s[4:5]
	v_mov_b32_e32 v2, s4
	v_readlane_b32 s4, v254, 35
	v_readlane_b32 s5, v254, 36
	s_nop 4
	global_atomic_add v2, v201, v2, s[4:5] sc0

.Lxl_5:
	s_mov_b64 s[4:5], exec
	v_mbcnt_lo_u32_b32 v0, s4, 0
	v_mbcnt_hi_u32_b32 v0, s5, v0
	v_cmp_eq_u32_e32 vcc, 0, v0
	s_waitcnt vmcnt(0)
	buffer_inv sc1
	s_and_saveexec_b64 s[6:7], vcc
	s_cbranch_execz .LBB0_702
	s_bcnt1_i32_b64 s4, s[4:5]
	v_mov_b32_e32 v0, s4
	v_readlane_b32 s4, v254, 33
	v_readlane_b32 s5, v254, 34
	s_nop 4
	global_atomic_add v201, v0, s[4:5]
